# v48 + 64-byte alignment of the 16 GEMM K-loop header labels (p2align 6)
# speedup vs baseline: 1.0015x; 1.0015x over previous
.LBB0_169:
	s_ashr_i32 s45, s44, 31
	s_lshl_b64 s[34:35], s[44:45], 19
	s_add_u32 s46, s25, s34
	s_addc_u32 s47, s27, s35
	s_and_b64 s[34:35], s[4:5], exec
	s_cselect_b32 s7, s47, s51
	s_cselect_b32 s34, s46, s50
	s_ashr_i32 s43, s42, 31
	s_lshl_b64 s[48:49], s[42:43], 19
	s_add_u32 s48, s37, s48
	s_addc_u32 s49, s39, s49
	s_and_b64 s[54:55], s[4:5], exec
	s_cselect_b32 s35, s49, s53
	s_cselect_b32 s43, s48, s52
	s_add_u32 s50, s50, 0x40080
	s_addc_u32 s51, s51, 0
	s_add_u32 s33, s52, 0x100
	v_mov_b64_e32 v[0:1], 0
	s_addc_u32 s45, s53, 0
	s_mov_b32 s67, -2
	s_waitcnt lgkmcnt(0)
	v_mov_b64_e32 v[2:3], 0
	v_mov_b64_e32 v[4:5], 0
	v_mov_b64_e32 v[6:7], 0
	v_mov_b64_e32 v[16:17], 0
	v_mov_b64_e32 v[18:19], 0
	v_mov_b64_e32 v[20:21], 0
	v_mov_b64_e32 v[22:23], 0
	v_mov_b64_e32 v[32:33], 0
	v_mov_b64_e32 v[34:35], 0
	v_mov_b64_e32 v[36:37], 0
	v_mov_b64_e32 v[38:39], 0
	v_mov_b64_e32 v[48:49], 0
	v_mov_b64_e32 v[50:51], 0
	v_mov_b64_e32 v[52:53], 0
	v_mov_b64_e32 v[54:55], 0
	v_mov_b64_e32 v[8:9], 0
	v_mov_b64_e32 v[10:11], 0
	v_mov_b64_e32 v[12:13], 0
	v_mov_b64_e32 v[14:15], 0
	v_mov_b64_e32 v[24:25], 0
	v_mov_b64_e32 v[26:27], 0
	v_mov_b64_e32 v[28:29], 0
	v_mov_b64_e32 v[30:31], 0
	v_mov_b64_e32 v[40:41], 0
	v_mov_b64_e32 v[42:43], 0
	v_mov_b64_e32 v[44:45], 0
	v_mov_b64_e32 v[46:47], 0
	v_mov_b64_e32 v[56:57], 0
	v_mov_b64_e32 v[58:59], 0
	v_mov_b64_e32 v[60:61], 0
	v_mov_b64_e32 v[62:63], 0
	v_mov_b64_e32 v[64:65], 0
	v_mov_b64_e32 v[66:67], 0
	v_mov_b64_e32 v[68:69], 0
	v_mov_b64_e32 v[70:71], 0
	v_mov_b64_e32 v[80:81], 0
	v_mov_b64_e32 v[82:83], 0
	v_mov_b64_e32 v[84:85], 0
	v_mov_b64_e32 v[86:87], 0
	v_mov_b64_e32 v[96:97], 0
	v_mov_b64_e32 v[98:99], 0
	v_mov_b64_e32 v[100:101], 0
	v_mov_b64_e32 v[102:103], 0
	v_mov_b64_e32 v[112:113], 0
	v_mov_b64_e32 v[114:115], 0
	v_mov_b64_e32 v[116:117], 0
	v_mov_b64_e32 v[118:119], 0
	v_mov_b64_e32 v[72:73], 0
	v_mov_b64_e32 v[74:75], 0
	v_mov_b64_e32 v[76:77], 0
	v_mov_b64_e32 v[78:79], 0
	v_mov_b64_e32 v[88:89], 0
	v_mov_b64_e32 v[90:91], 0
	v_mov_b64_e32 v[92:93], 0
	v_mov_b64_e32 v[94:95], 0
	v_mov_b64_e32 v[104:105], 0
	v_mov_b64_e32 v[106:107], 0
	v_mov_b64_e32 v[108:109], 0
	v_mov_b64_e32 v[110:111], 0
	v_mov_b64_e32 v[120:121], 0
	v_mov_b64_e32 v[122:123], 0
	v_mov_b64_e32 v[124:125], 0
	v_mov_b64_e32 v[126:127], 0
	.p2align	6

.LBB0_390:
	s_cmp_lg_u32 s33, 0
	s_cselect_b64 s[46:47], -1, 0
	s_and_b64 s[34:35], s[46:47], exec
	s_cselect_b32 s34, s33, 48
	s_cmp_lt_i32 s34, 1
	s_cbranch_scc1 .LBB0_402
	s_add_i32 s33, s34, -2
	s_add_u32 s35, s50, 0x100
	v_mov_b64_e32 v[0:1], 0
	s_addc_u32 s91, s51, 0
	s_mov_b32 s52, 0
	v_mov_b64_e32 v[2:3], 0
	v_mov_b64_e32 v[4:5], 0
	v_mov_b64_e32 v[6:7], 0
	v_mov_b64_e32 v[16:17], 0
	v_mov_b64_e32 v[18:19], 0
	v_mov_b64_e32 v[20:21], 0
	v_mov_b64_e32 v[22:23], 0
	v_mov_b64_e32 v[32:33], 0
	v_mov_b64_e32 v[34:35], 0
	v_mov_b64_e32 v[36:37], 0
	v_mov_b64_e32 v[38:39], 0
	v_mov_b64_e32 v[48:49], 0
	v_mov_b64_e32 v[50:51], 0
	v_mov_b64_e32 v[52:53], 0
	v_mov_b64_e32 v[54:55], 0
	v_mov_b64_e32 v[8:9], 0
	v_mov_b64_e32 v[10:11], 0
	v_mov_b64_e32 v[12:13], 0
	v_mov_b64_e32 v[14:15], 0
	v_mov_b64_e32 v[24:25], 0
	v_mov_b64_e32 v[26:27], 0
	v_mov_b64_e32 v[28:29], 0
	v_mov_b64_e32 v[30:31], 0
	v_mov_b64_e32 v[40:41], 0
	v_mov_b64_e32 v[42:43], 0
	v_mov_b64_e32 v[44:45], 0
	v_mov_b64_e32 v[46:47], 0
	v_mov_b64_e32 v[56:57], 0
	v_mov_b64_e32 v[58:59], 0
	v_mov_b64_e32 v[60:61], 0
	v_mov_b64_e32 v[62:63], 0
	v_mov_b64_e32 v[64:65], 0
	v_mov_b64_e32 v[66:67], 0
	v_mov_b64_e32 v[68:69], 0
	v_mov_b64_e32 v[70:71], 0
	v_mov_b64_e32 v[80:81], 0
	v_mov_b64_e32 v[82:83], 0
	v_mov_b64_e32 v[84:85], 0
	v_mov_b64_e32 v[86:87], 0
	v_mov_b64_e32 v[96:97], 0
	v_mov_b64_e32 v[98:99], 0
	v_mov_b64_e32 v[100:101], 0
	v_mov_b64_e32 v[102:103], 0
	v_mov_b64_e32 v[112:113], 0
	v_mov_b64_e32 v[114:115], 0
	v_mov_b64_e32 v[116:117], 0
	v_mov_b64_e32 v[118:119], 0
	v_mov_b64_e32 v[72:73], 0
	v_mov_b64_e32 v[74:75], 0
	v_mov_b64_e32 v[76:77], 0
	v_mov_b64_e32 v[78:79], 0
	v_mov_b64_e32 v[88:89], 0
	v_mov_b64_e32 v[90:91], 0
	v_mov_b64_e32 v[92:93], 0
	v_mov_b64_e32 v[94:95], 0
	v_mov_b64_e32 v[104:105], 0
	v_mov_b64_e32 v[106:107], 0
	v_mov_b64_e32 v[108:109], 0
	v_mov_b64_e32 v[110:111], 0
	v_mov_b64_e32 v[120:121], 0
	v_mov_b64_e32 v[122:123], 0
	v_mov_b64_e32 v[124:125], 0
	v_mov_b64_e32 v[126:127], 0
	.p2align	6

.LBB0_530:
	s_ashr_i32 s17, s16, 31
	s_lshl_b64 s[18:19], s[16:17], 19
	s_add_u32 s18, s39, s18
	s_addc_u32 s19, s40, s19
	s_and_b64 s[20:21], s[2:3], exec
	s_cselect_b32 s17, s19, s25
	s_cselect_b32 s34, s18, s24
	s_ashr_i32 s15, s14, 31
	s_lshl_b64 s[20:21], s[14:15], 19
	s_add_u32 s20, s41, s20
	s_addc_u32 s21, s42, s21
	s_and_b64 s[36:37], s[2:3], exec
	s_cselect_b32 s15, s21, s27
	s_cselect_b32 s35, s20, s26
	s_add_u32 s24, s24, 0x40080
	s_addc_u32 s25, s25, 0
	s_add_u32 s33, s26, 0x100
	v_mov_b64_e32 v[0:1], 0
	s_addc_u32 s56, s27, 0
	s_mov_b32 s57, -2
	v_mov_b64_e32 v[2:3], 0
	v_mov_b64_e32 v[4:5], 0
	v_mov_b64_e32 v[6:7], 0
	v_mov_b64_e32 v[16:17], 0
	v_mov_b64_e32 v[18:19], 0
	v_mov_b64_e32 v[20:21], 0
	v_mov_b64_e32 v[22:23], 0
	v_mov_b64_e32 v[32:33], 0
	v_mov_b64_e32 v[34:35], 0
	v_mov_b64_e32 v[36:37], 0
	v_mov_b64_e32 v[38:39], 0
	v_mov_b64_e32 v[48:49], 0
	v_mov_b64_e32 v[50:51], 0
	v_mov_b64_e32 v[52:53], 0
	v_mov_b64_e32 v[54:55], 0
	v_mov_b64_e32 v[8:9], 0
	v_mov_b64_e32 v[10:11], 0
	v_mov_b64_e32 v[12:13], 0
	v_mov_b64_e32 v[14:15], 0
	v_mov_b64_e32 v[24:25], 0
	v_mov_b64_e32 v[26:27], 0
	v_mov_b64_e32 v[28:29], 0
	v_mov_b64_e32 v[30:31], 0
	v_mov_b64_e32 v[40:41], 0
	v_mov_b64_e32 v[42:43], 0
	v_mov_b64_e32 v[44:45], 0
	v_mov_b64_e32 v[46:47], 0
	v_mov_b64_e32 v[56:57], 0
	v_mov_b64_e32 v[58:59], 0
	v_mov_b64_e32 v[60:61], 0
	v_mov_b64_e32 v[62:63], 0
	v_mov_b64_e32 v[64:65], 0
	v_mov_b64_e32 v[66:67], 0
	v_mov_b64_e32 v[68:69], 0
	v_mov_b64_e32 v[70:71], 0
	v_mov_b64_e32 v[80:81], 0
	v_mov_b64_e32 v[82:83], 0
	v_mov_b64_e32 v[84:85], 0
	v_mov_b64_e32 v[86:87], 0
	v_mov_b64_e32 v[96:97], 0
	v_mov_b64_e32 v[98:99], 0
	v_mov_b64_e32 v[100:101], 0
	v_mov_b64_e32 v[102:103], 0
	v_mov_b64_e32 v[112:113], 0
	v_mov_b64_e32 v[114:115], 0
	v_mov_b64_e32 v[116:117], 0
	v_mov_b64_e32 v[118:119], 0
	v_mov_b64_e32 v[72:73], 0
	v_mov_b64_e32 v[74:75], 0
	v_mov_b64_e32 v[76:77], 0
	v_mov_b64_e32 v[78:79], 0
	v_mov_b64_e32 v[88:89], 0
	v_mov_b64_e32 v[90:91], 0
	v_mov_b64_e32 v[92:93], 0
	v_mov_b64_e32 v[94:95], 0
	v_mov_b64_e32 v[104:105], 0
	v_mov_b64_e32 v[106:107], 0
	v_mov_b64_e32 v[108:109], 0
	v_mov_b64_e32 v[110:111], 0
	v_mov_b64_e32 v[120:121], 0
	v_mov_b64_e32 v[122:123], 0
	v_mov_b64_e32 v[124:125], 0
	v_mov_b64_e32 v[126:127], 0
	.p2align	6

.LBB0_609:
	s_cmp_lg_u32 s33, 0
	s_cselect_b64 s[46:47], -1, 0
	s_and_b64 s[34:35], s[46:47], exec
	s_cselect_b32 s34, s33, 44
	s_cmp_lt_i32 s34, 1
	s_cbranch_scc1 .LBB0_621
	s_add_i32 s33, s34, -2
	s_add_u32 s35, s50, 0x100
	v_mov_b64_e32 v[0:1], 0
	s_addc_u32 s91, s51, 0
	s_mov_b32 s52, 0
	v_mov_b64_e32 v[2:3], 0
	v_mov_b64_e32 v[4:5], 0
	v_mov_b64_e32 v[6:7], 0
	v_mov_b64_e32 v[16:17], 0
	v_mov_b64_e32 v[18:19], 0
	v_mov_b64_e32 v[20:21], 0
	v_mov_b64_e32 v[22:23], 0
	v_mov_b64_e32 v[32:33], 0
	v_mov_b64_e32 v[34:35], 0
	v_mov_b64_e32 v[36:37], 0
	v_mov_b64_e32 v[38:39], 0
	v_mov_b64_e32 v[48:49], 0
	v_mov_b64_e32 v[50:51], 0
	v_mov_b64_e32 v[52:53], 0
	v_mov_b64_e32 v[54:55], 0
	v_mov_b64_e32 v[8:9], 0
	v_mov_b64_e32 v[10:11], 0
	v_mov_b64_e32 v[12:13], 0
	v_mov_b64_e32 v[14:15], 0
	v_mov_b64_e32 v[24:25], 0
	v_mov_b64_e32 v[26:27], 0
	v_mov_b64_e32 v[28:29], 0
	v_mov_b64_e32 v[30:31], 0
	v_mov_b64_e32 v[40:41], 0
	v_mov_b64_e32 v[42:43], 0
	v_mov_b64_e32 v[44:45], 0
	v_mov_b64_e32 v[46:47], 0
	v_mov_b64_e32 v[56:57], 0
	v_mov_b64_e32 v[58:59], 0
	v_mov_b64_e32 v[60:61], 0
	v_mov_b64_e32 v[62:63], 0
	v_mov_b64_e32 v[64:65], 0
	v_mov_b64_e32 v[66:67], 0
	v_mov_b64_e32 v[68:69], 0
	v_mov_b64_e32 v[70:71], 0
	v_mov_b64_e32 v[80:81], 0
	v_mov_b64_e32 v[82:83], 0
	v_mov_b64_e32 v[84:85], 0
	v_mov_b64_e32 v[86:87], 0
	v_mov_b64_e32 v[96:97], 0
	v_mov_b64_e32 v[98:99], 0
	v_mov_b64_e32 v[100:101], 0
	v_mov_b64_e32 v[102:103], 0
	v_mov_b64_e32 v[112:113], 0
	v_mov_b64_e32 v[114:115], 0
	v_mov_b64_e32 v[116:117], 0
	v_mov_b64_e32 v[118:119], 0
	v_mov_b64_e32 v[72:73], 0
	v_mov_b64_e32 v[74:75], 0
	v_mov_b64_e32 v[76:77], 0
	v_mov_b64_e32 v[78:79], 0
	v_mov_b64_e32 v[88:89], 0
	v_mov_b64_e32 v[90:91], 0
	v_mov_b64_e32 v[92:93], 0
	v_mov_b64_e32 v[94:95], 0
	v_mov_b64_e32 v[104:105], 0
	v_mov_b64_e32 v[106:107], 0
	v_mov_b64_e32 v[108:109], 0
	v_mov_b64_e32 v[110:111], 0
	v_mov_b64_e32 v[120:121], 0
	v_mov_b64_e32 v[122:123], 0
	v_mov_b64_e32 v[124:125], 0
	v_mov_b64_e32 v[126:127], 0
	.p2align	6

.LBB0_747:
	s_ashr_i32 s39, s38, 31
	s_lshl_b64 s[34:35], s[38:39], 19
	s_add_u32 s40, s51, s34
	s_addc_u32 s41, s52, s35
	s_and_b64 s[34:35], s[2:3], exec
	s_cselect_b32 s5, s41, s45
	s_cselect_b32 s34, s40, s44
	s_ashr_i32 s37, s36, 31
	s_lshl_b64 s[42:43], s[36:37], 19
	s_add_u32 s42, s53, s42
	s_addc_u32 s43, s54, s43
	s_and_b64 s[48:49], s[2:3], exec
	s_cselect_b32 s35, s43, s47
	s_cselect_b32 s37, s42, s46
	s_add_u32 s44, s44, 0x40080
	s_addc_u32 s45, s45, 0
	s_add_u32 s33, s46, 0x100
	v_mov_b64_e32 v[0:1], 0
	s_addc_u32 s39, s47, 0
	s_mov_b32 s75, -2
	v_mov_b64_e32 v[2:3], 0
	v_mov_b64_e32 v[4:5], 0
	v_mov_b64_e32 v[6:7], 0
	v_mov_b64_e32 v[16:17], 0
	v_mov_b64_e32 v[18:19], 0
	v_mov_b64_e32 v[20:21], 0
	v_mov_b64_e32 v[22:23], 0
	v_mov_b64_e32 v[32:33], 0
	v_mov_b64_e32 v[34:35], 0
	v_mov_b64_e32 v[36:37], 0
	v_mov_b64_e32 v[38:39], 0
	v_mov_b64_e32 v[48:49], 0
	v_mov_b64_e32 v[50:51], 0
	v_mov_b64_e32 v[52:53], 0
	v_mov_b64_e32 v[54:55], 0
	v_mov_b64_e32 v[8:9], 0
	v_mov_b64_e32 v[10:11], 0
	v_mov_b64_e32 v[12:13], 0
	v_mov_b64_e32 v[14:15], 0
	v_mov_b64_e32 v[24:25], 0
	v_mov_b64_e32 v[26:27], 0
	v_mov_b64_e32 v[28:29], 0
	v_mov_b64_e32 v[30:31], 0
	v_mov_b64_e32 v[40:41], 0
	v_mov_b64_e32 v[42:43], 0
	v_mov_b64_e32 v[44:45], 0
	v_mov_b64_e32 v[46:47], 0
	v_mov_b64_e32 v[56:57], 0
	v_mov_b64_e32 v[58:59], 0
	v_mov_b64_e32 v[60:61], 0
	v_mov_b64_e32 v[62:63], 0
	v_mov_b64_e32 v[64:65], 0
	v_mov_b64_e32 v[66:67], 0
	v_mov_b64_e32 v[68:69], 0
	v_mov_b64_e32 v[70:71], 0
	v_mov_b64_e32 v[80:81], 0
	v_mov_b64_e32 v[82:83], 0
	v_mov_b64_e32 v[84:85], 0
	v_mov_b64_e32 v[86:87], 0
	v_mov_b64_e32 v[96:97], 0
	v_mov_b64_e32 v[98:99], 0
	v_mov_b64_e32 v[100:101], 0
	v_mov_b64_e32 v[102:103], 0
	v_mov_b64_e32 v[112:113], 0
	v_mov_b64_e32 v[114:115], 0
	v_mov_b64_e32 v[116:117], 0
	v_mov_b64_e32 v[118:119], 0
	v_mov_b64_e32 v[72:73], 0
	v_mov_b64_e32 v[74:75], 0
	v_mov_b64_e32 v[76:77], 0
	v_mov_b64_e32 v[78:79], 0
	v_mov_b64_e32 v[88:89], 0
	v_mov_b64_e32 v[90:91], 0
	v_mov_b64_e32 v[92:93], 0
	v_mov_b64_e32 v[94:95], 0
	v_mov_b64_e32 v[104:105], 0
	v_mov_b64_e32 v[106:107], 0
	v_mov_b64_e32 v[108:109], 0
	v_mov_b64_e32 v[110:111], 0
	v_mov_b64_e32 v[120:121], 0
	v_mov_b64_e32 v[122:123], 0
	v_mov_b64_e32 v[124:125], 0
	v_mov_b64_e32 v[126:127], 0
	.p2align	6

.LBB0_1114:
	s_cmp_lg_u32 s33, 0
	s_cselect_b64 s[54:55], -1, 0
	s_and_b64 s[34:35], s[54:55], exec
	s_cselect_b32 s19, s33, 16
	s_cmp_lt_i32 s19, 1
	s_cbranch_scc1 .LBB0_1126
	s_add_i32 s34, s19, -2
	s_add_u32 s56, s56, 0x40080
	s_addc_u32 s57, s57, 0
	s_add_u32 s33, s58, 0x100
	v_mov_b64_e32 v[0:1], 0
	s_addc_u32 s35, s59, 0
	s_mov_b32 s47, 0
	v_mov_b64_e32 v[2:3], 0
	v_mov_b64_e32 v[4:5], 0
	v_mov_b64_e32 v[6:7], 0
	v_mov_b64_e32 v[16:17], 0
	v_mov_b64_e32 v[18:19], 0
	v_mov_b64_e32 v[20:21], 0
	v_mov_b64_e32 v[22:23], 0
	v_mov_b64_e32 v[32:33], 0
	v_mov_b64_e32 v[34:35], 0
	v_mov_b64_e32 v[36:37], 0
	v_mov_b64_e32 v[38:39], 0
	v_mov_b64_e32 v[48:49], 0
	v_mov_b64_e32 v[50:51], 0
	v_mov_b64_e32 v[52:53], 0
	v_mov_b64_e32 v[54:55], 0
	v_mov_b64_e32 v[8:9], 0
	v_mov_b64_e32 v[10:11], 0
	v_mov_b64_e32 v[12:13], 0
	v_mov_b64_e32 v[14:15], 0
	v_mov_b64_e32 v[24:25], 0
	v_mov_b64_e32 v[26:27], 0
	v_mov_b64_e32 v[28:29], 0
	v_mov_b64_e32 v[30:31], 0
	v_mov_b64_e32 v[40:41], 0
	v_mov_b64_e32 v[42:43], 0
	v_mov_b64_e32 v[44:45], 0
	v_mov_b64_e32 v[46:47], 0
	v_mov_b64_e32 v[56:57], 0
	v_mov_b64_e32 v[58:59], 0
	v_mov_b64_e32 v[60:61], 0
	v_mov_b64_e32 v[62:63], 0
	v_mov_b64_e32 v[64:65], 0
	v_mov_b64_e32 v[66:67], 0
	v_mov_b64_e32 v[68:69], 0
	v_mov_b64_e32 v[70:71], 0
	v_mov_b64_e32 v[80:81], 0
	v_mov_b64_e32 v[82:83], 0
	v_mov_b64_e32 v[84:85], 0
	v_mov_b64_e32 v[86:87], 0
	v_mov_b64_e32 v[96:97], 0
	v_mov_b64_e32 v[98:99], 0
	v_mov_b64_e32 v[100:101], 0
	v_mov_b64_e32 v[102:103], 0
	v_mov_b64_e32 v[112:113], 0
	v_mov_b64_e32 v[114:115], 0
	v_mov_b64_e32 v[116:117], 0
	v_mov_b64_e32 v[118:119], 0
	v_mov_b64_e32 v[72:73], 0
	v_mov_b64_e32 v[74:75], 0
	v_mov_b64_e32 v[76:77], 0
	v_mov_b64_e32 v[78:79], 0
	v_mov_b64_e32 v[88:89], 0
	v_mov_b64_e32 v[90:91], 0
	v_mov_b64_e32 v[92:93], 0
	v_mov_b64_e32 v[94:95], 0
	v_mov_b64_e32 v[104:105], 0
	v_mov_b64_e32 v[106:107], 0
	v_mov_b64_e32 v[108:109], 0
	v_mov_b64_e32 v[110:111], 0
	v_mov_b64_e32 v[120:121], 0
	v_mov_b64_e32 v[122:123], 0
	v_mov_b64_e32 v[124:125], 0
	v_mov_b64_e32 v[126:127], 0
	.p2align	6

.LBB0_1471:
	s_ashr_i32 s41, s40, 31
	s_lshl_b64 s[10:11], s[40:41], 19
	s_add_u32 s42, s51, s10
	s_addc_u32 s43, s52, s11
	s_and_b64 s[10:11], s[2:3], exec
	s_cselect_b32 s5, s43, s7
	s_cselect_b32 s13, s42, s6
	s_ashr_i32 s39, s38, 31
	s_lshl_b64 s[10:11], s[38:39], 19
	s_add_u32 s44, s53, s10
	s_addc_u32 s45, s54, s11
	s_and_b64 s[10:11], s[2:3], exec
	s_cselect_b32 s16, s45, s9
	s_cselect_b32 s34, s44, s8
	s_add_u32 s6, s6, 0x40080
	s_addc_u32 s7, s7, 0
	s_add_u32 s33, s8, 0x100
	v_mov_b64_e32 v[0:1], 0
	s_addc_u32 s35, s9, 0
	s_mov_b32 s39, -2
	v_mov_b64_e32 v[2:3], 0
	v_mov_b64_e32 v[4:5], 0
	v_mov_b64_e32 v[6:7], 0
	v_mov_b64_e32 v[16:17], 0
	v_mov_b64_e32 v[18:19], 0
	v_mov_b64_e32 v[20:21], 0
	v_mov_b64_e32 v[22:23], 0
	v_mov_b64_e32 v[32:33], 0
	v_mov_b64_e32 v[34:35], 0
	v_mov_b64_e32 v[36:37], 0
	v_mov_b64_e32 v[38:39], 0
	v_mov_b64_e32 v[48:49], 0
	v_mov_b64_e32 v[50:51], 0
	v_mov_b64_e32 v[52:53], 0
	v_mov_b64_e32 v[54:55], 0
	v_mov_b64_e32 v[8:9], 0
	v_mov_b64_e32 v[10:11], 0
	v_mov_b64_e32 v[12:13], 0
	v_mov_b64_e32 v[14:15], 0
	v_mov_b64_e32 v[24:25], 0
	v_mov_b64_e32 v[26:27], 0
	v_mov_b64_e32 v[28:29], 0
	v_mov_b64_e32 v[30:31], 0
	v_mov_b64_e32 v[40:41], 0
	v_mov_b64_e32 v[42:43], 0
	v_mov_b64_e32 v[44:45], 0
	v_mov_b64_e32 v[46:47], 0
	v_mov_b64_e32 v[56:57], 0
	v_mov_b64_e32 v[58:59], 0
	v_mov_b64_e32 v[60:61], 0
	v_mov_b64_e32 v[62:63], 0
	v_mov_b64_e32 v[64:65], 0
	v_mov_b64_e32 v[66:67], 0
	v_mov_b64_e32 v[68:69], 0
	v_mov_b64_e32 v[70:71], 0
	v_mov_b64_e32 v[80:81], 0
	v_mov_b64_e32 v[82:83], 0
	v_mov_b64_e32 v[84:85], 0
	v_mov_b64_e32 v[86:87], 0
	v_mov_b64_e32 v[96:97], 0
	v_mov_b64_e32 v[98:99], 0
	v_mov_b64_e32 v[100:101], 0
	v_mov_b64_e32 v[102:103], 0
	v_mov_b64_e32 v[112:113], 0
	v_mov_b64_e32 v[114:115], 0
	v_mov_b64_e32 v[116:117], 0
	v_mov_b64_e32 v[118:119], 0
	v_mov_b64_e32 v[72:73], 0
	v_mov_b64_e32 v[74:75], 0
	v_mov_b64_e32 v[76:77], 0
	v_mov_b64_e32 v[78:79], 0
	v_mov_b64_e32 v[88:89], 0
	v_mov_b64_e32 v[90:91], 0
	v_mov_b64_e32 v[92:93], 0
	v_mov_b64_e32 v[94:95], 0
	v_mov_b64_e32 v[104:105], 0
	v_mov_b64_e32 v[106:107], 0
	v_mov_b64_e32 v[108:109], 0
	v_mov_b64_e32 v[110:111], 0
	v_mov_b64_e32 v[120:121], 0
	v_mov_b64_e32 v[122:123], 0
	v_mov_b64_e32 v[124:125], 0
	v_mov_b64_e32 v[126:127], 0
	.p2align	6

.LBB0_1947:
	s_cmp_lg_u32 s33, 0
	s_cselect_b64 s[54:55], -1, 0
	s_and_b64 s[34:35], s[54:55], exec
	s_cselect_b32 s19, s33, 32
	s_cmp_lt_i32 s19, 1
	s_cbranch_scc1 .LBB0_1959
	s_add_i32 s34, s19, -2
	s_add_u32 s56, s56, 0x80080
	s_addc_u32 s57, s57, 0
	s_add_u32 s33, s58, 0x100
	v_mov_b64_e32 v[0:1], 0
	s_addc_u32 s35, s59, 0
	s_mov_b32 s47, 0
	v_mov_b64_e32 v[2:3], 0
	v_mov_b64_e32 v[4:5], 0
	v_mov_b64_e32 v[6:7], 0
	v_mov_b64_e32 v[16:17], 0
	v_mov_b64_e32 v[18:19], 0
	v_mov_b64_e32 v[20:21], 0
	v_mov_b64_e32 v[22:23], 0
	v_mov_b64_e32 v[32:33], 0
	v_mov_b64_e32 v[34:35], 0
	v_mov_b64_e32 v[36:37], 0
	v_mov_b64_e32 v[38:39], 0
	v_mov_b64_e32 v[48:49], 0
	v_mov_b64_e32 v[50:51], 0
	v_mov_b64_e32 v[52:53], 0
	v_mov_b64_e32 v[54:55], 0
	v_mov_b64_e32 v[8:9], 0
	v_mov_b64_e32 v[10:11], 0
	v_mov_b64_e32 v[12:13], 0
	v_mov_b64_e32 v[14:15], 0
	v_mov_b64_e32 v[24:25], 0
	v_mov_b64_e32 v[26:27], 0
	v_mov_b64_e32 v[28:29], 0
	v_mov_b64_e32 v[30:31], 0
	v_mov_b64_e32 v[40:41], 0
	v_mov_b64_e32 v[42:43], 0
	v_mov_b64_e32 v[44:45], 0
	v_mov_b64_e32 v[46:47], 0
	v_mov_b64_e32 v[56:57], 0
	v_mov_b64_e32 v[58:59], 0
	v_mov_b64_e32 v[60:61], 0
	v_mov_b64_e32 v[62:63], 0
	v_mov_b64_e32 v[64:65], 0
	v_mov_b64_e32 v[66:67], 0
	v_mov_b64_e32 v[68:69], 0
	v_mov_b64_e32 v[70:71], 0
	v_mov_b64_e32 v[80:81], 0
	v_mov_b64_e32 v[82:83], 0
	v_mov_b64_e32 v[84:85], 0
	v_mov_b64_e32 v[86:87], 0
	v_mov_b64_e32 v[96:97], 0
	v_mov_b64_e32 v[98:99], 0
	v_mov_b64_e32 v[100:101], 0
	v_mov_b64_e32 v[102:103], 0
	v_mov_b64_e32 v[112:113], 0
	v_mov_b64_e32 v[114:115], 0
	v_mov_b64_e32 v[116:117], 0
	v_mov_b64_e32 v[118:119], 0
	v_mov_b64_e32 v[72:73], 0
	v_mov_b64_e32 v[74:75], 0
	v_mov_b64_e32 v[76:77], 0
	v_mov_b64_e32 v[78:79], 0
	v_mov_b64_e32 v[88:89], 0
	v_mov_b64_e32 v[90:91], 0
	v_mov_b64_e32 v[92:93], 0
	v_mov_b64_e32 v[94:95], 0
	v_mov_b64_e32 v[104:105], 0
	v_mov_b64_e32 v[106:107], 0
	v_mov_b64_e32 v[108:109], 0
	v_mov_b64_e32 v[110:111], 0
	v_mov_b64_e32 v[120:121], 0
	v_mov_b64_e32 v[122:123], 0
	v_mov_b64_e32 v[124:125], 0
	v_mov_b64_e32 v[126:127], 0
	.p2align	6

.LBB0_2304:
	s_ashr_i32 s59, s58, 31
	s_lshl_b64 s[34:35], s[58:59], 19
	s_add_u32 s60, s41, s34
	s_addc_u32 s61, s43, s35
	s_and_b64 s[34:35], s[4:5], exec
	s_cselect_b32 s9, s61, s7
	s_cselect_b32 s34, s60, s6
	s_ashr_i32 s57, s56, 31
	s_lshl_b64 s[62:63], s[56:57], 19
	s_add_u32 s62, s45, s62
	s_addc_u32 s63, s47, s63
	s_and_b64 s[68:69], s[4:5], exec
	s_cselect_b32 s35, s63, s67
	s_cselect_b32 s57, s62, s66
	s_add_u32 s6, s6, 0x40080
	s_addc_u32 s7, s7, 0
	s_add_u32 s33, s66, 0x100
	v_mov_b64_e32 v[0:1], 0
	s_addc_u32 s59, s67, 0
	s_mov_b32 s96, -2
	v_mov_b64_e32 v[2:3], 0
	v_mov_b64_e32 v[4:5], 0
	v_mov_b64_e32 v[6:7], 0
	v_mov_b64_e32 v[16:17], 0
	v_mov_b64_e32 v[18:19], 0
	v_mov_b64_e32 v[20:21], 0
	v_mov_b64_e32 v[22:23], 0
	v_mov_b64_e32 v[32:33], 0
	v_mov_b64_e32 v[34:35], 0
	v_mov_b64_e32 v[36:37], 0
	v_mov_b64_e32 v[38:39], 0
	v_mov_b64_e32 v[48:49], 0
	v_mov_b64_e32 v[50:51], 0
	v_mov_b64_e32 v[52:53], 0
	v_mov_b64_e32 v[54:55], 0
	v_mov_b64_e32 v[8:9], 0
	v_mov_b64_e32 v[10:11], 0
	v_mov_b64_e32 v[12:13], 0
	v_mov_b64_e32 v[14:15], 0
	v_mov_b64_e32 v[24:25], 0
	v_mov_b64_e32 v[26:27], 0
	v_mov_b64_e32 v[28:29], 0
	v_mov_b64_e32 v[30:31], 0
	v_mov_b64_e32 v[40:41], 0
	v_mov_b64_e32 v[42:43], 0
	v_mov_b64_e32 v[44:45], 0
	v_mov_b64_e32 v[46:47], 0
	v_mov_b64_e32 v[56:57], 0
	v_mov_b64_e32 v[58:59], 0
	v_mov_b64_e32 v[60:61], 0
	v_mov_b64_e32 v[62:63], 0
	v_mov_b64_e32 v[64:65], 0
	v_mov_b64_e32 v[66:67], 0
	v_mov_b64_e32 v[68:69], 0
	v_mov_b64_e32 v[70:71], 0
	v_mov_b64_e32 v[80:81], 0
	v_mov_b64_e32 v[82:83], 0
	v_mov_b64_e32 v[84:85], 0
	v_mov_b64_e32 v[86:87], 0
	v_mov_b64_e32 v[96:97], 0
	v_mov_b64_e32 v[98:99], 0
	v_mov_b64_e32 v[100:101], 0
	v_mov_b64_e32 v[102:103], 0
	v_mov_b64_e32 v[112:113], 0
	v_mov_b64_e32 v[114:115], 0
	v_mov_b64_e32 v[116:117], 0
	v_mov_b64_e32 v[118:119], 0
	v_mov_b64_e32 v[72:73], 0
	v_mov_b64_e32 v[74:75], 0
	v_mov_b64_e32 v[76:77], 0
	v_mov_b64_e32 v[78:79], 0
	v_mov_b64_e32 v[88:89], 0
	v_mov_b64_e32 v[90:91], 0
	v_mov_b64_e32 v[92:93], 0
	v_mov_b64_e32 v[94:95], 0
	v_mov_b64_e32 v[104:105], 0
	v_mov_b64_e32 v[106:107], 0
	v_mov_b64_e32 v[108:109], 0
	v_mov_b64_e32 v[110:111], 0
	v_mov_b64_e32 v[120:121], 0
	v_mov_b64_e32 v[122:123], 0
	v_mov_b64_e32 v[124:125], 0
	v_mov_b64_e32 v[126:127], 0
	.p2align	6
